# baseline (speedup 1.0000x reference)
; __device__ __forceinline__ unsigned xb_ld(unsigned* p)              { return __hip_atomic_load(p, __ATOMIC_RELAXED, __HIP_MEMORY_SCOPE_AGENT); }
; __device__ __forceinline__ unsigned xb_add(unsigned* p, unsigned v) { return __hip_atomic_fetch_add(p, v, __ATOMIC_RELAXED, __HIP_MEMORY_SCOPE_AGENT); }
; #define XB_SPIN(cond, bar) do { unsigned _sp = 0; while (cond) { __builtin_amdgcn_s_sleep(1); \
;     if ((++_sp & 255u) == 0u) { if (xb_ld(&(bar)[XB_TMO])) break; if (_sp > XB_SPIN_CAP) { atomicAdd(&(bar)[XB_TMO], 1u); break; } } } } while (0)
; __device__ __forceinline__ void xcd_barrier(XcdBarrier& b) {
;     ...
;         const unsigned old = xb_add(&bar[XB_XSUB(bx)], 1u);
;         const unsigned gen = b.gen;
;         if (old + 1u == (gen + 1u) * b.nloc) {
;             __builtin_amdgcn_fence(__ATOMIC_RELEASE, "agent");
;             asm volatile("s_waitcnt vmcnt(0)" ::: "memory");
;             const unsigned og = xb_add(&bar[XB_TOP], 1u);
;             const unsigned tg = gen;
;             if (og + 1u == (tg + 1u) * b.nx) xb_add(&bar[XB_TOPGEN], 1u);
;             else XB_SPIN(xb_ld(&bar[XB_TOPGEN]) == tg, bar);
;             __builtin_amdgcn_fence(__ATOMIC_ACQUIRE, "agent");
;             xb_add(&bar[XB_XGEN(bx)], 1u);
;         } else {
;             XB_SPIN(xb_ld(&bar[XB_XGEN(bx)]) == gen, bar);
.LBB0_104:
	s_or_b64 exec, exec, s[4:5]
	s_waitcnt vmcnt(0)
	v_readfirstlane_b32 s2, v1
	s_nop 1
	v_add3_u32 v0, s2, v0, 1
	v_readlane_b32 s2, v252, 37
	s_nop 1
	v_cmp_ne_u32_e32 vcc, s2, v0
	s_and_saveexec_b64 s[2:3], vcc
	s_xor_b64 s[2:3], exec, s[2:3]
	s_cbranch_execz .LBB0_119
	s_movk_i32 s4, 0xd40
	s_mov_b32 s5, 0
	s_lshl_b64 s[4:5], s[4:5], 2
	s_add_u32 s4, s58, s4
	s_addc_u32 s5, s59, s5
	v_mov_b32_e32 v0, 0
	global_load_dword v1, v0, s[4:5] sc1
	s_waitcnt vmcnt(0)
	v_cmp_ne_u32_e32 vcc, 0, v1
	s_cbranch_vccnz .LBB0_118
	s_mov_b32 s12, 1
	s_branch .LBB0_108

; __device__ __forceinline__ unsigned xb_ld(unsigned* p)              { return __hip_atomic_load(p, __ATOMIC_RELAXED, __HIP_MEMORY_SCOPE_AGENT); }
; __device__ __forceinline__ unsigned xb_add(unsigned* p, unsigned v) { return __hip_atomic_fetch_add(p, v, __ATOMIC_RELAXED, __HIP_MEMORY_SCOPE_AGENT); }
; #define XB_SPIN(cond, bar) do { unsigned _sp = 0; while (cond) { __builtin_amdgcn_s_sleep(1); \
;     if ((++_sp & 255u) == 0u) { if (xb_ld(&(bar)[XB_TMO])) break; if (_sp > XB_SPIN_CAP) { atomicAdd(&(bar)[XB_TMO], 1u); break; } } } } while (0)
; __device__ __forceinline__ void xcd_barrier(XcdBarrier& b) {
;     ...
;         const unsigned old = xb_add(&bar[XB_XSUB(bx)], 1u);
;         const unsigned gen = b.gen;
;         if (old + 1u == (gen + 1u) * b.nloc) {
;             __builtin_amdgcn_fence(__ATOMIC_RELEASE, "agent");
;             asm volatile("s_waitcnt vmcnt(0)" ::: "memory");
;             const unsigned og = xb_add(&bar[XB_TOP], 1u);
;             const unsigned tg = gen;
;             if (og + 1u == (tg + 1u) * b.nx) xb_add(&bar[XB_TOPGEN], 1u);
;             else XB_SPIN(xb_ld(&bar[XB_TOPGEN]) == tg, bar);
;             __builtin_amdgcn_fence(__ATOMIC_ACQUIRE, "agent");
;             xb_add(&bar[XB_XGEN(bx)], 1u);
;         } else {
;             XB_SPIN(xb_ld(&bar[XB_XGEN(bx)]) == gen, bar);
.LBB0_211:
	s_or_b64 exec, exec, s[4:5]
	s_waitcnt vmcnt(0)
	v_readfirstlane_b32 s2, v2
	v_add_u32_e32 v16, 1, v191
	s_nop 0
	v_add3_u32 v0, s2, v0, 1
	v_readlane_b32 s2, v252, 37
	s_nop 1
	v_mul_lo_u32 v2, v16, s2
	v_cmp_ne_u32_e32 vcc, v0, v2
	s_and_saveexec_b64 s[2:3], vcc
	s_xor_b64 s[2:3], exec, s[2:3]
	s_cbranch_execz .LBB0_225
	v_readlane_b32 s4, v251, 18
	v_readlane_b32 s5, v251, 19
	s_mov_b32 s7, s5
	s_movk_i32 s6, 0xd40
	v_writelane_b32 v251, s4, 18
	s_nop 1
	v_writelane_b32 v251, s5, 19
	s_lshl_b64 s[4:5], s[6:7], 2
	s_add_u32 s6, s58, s4
	s_addc_u32 s7, s59, s5
	global_load_dword v0, v1, s[6:7] sc1
	s_waitcnt vmcnt(0)
	v_cmp_eq_u32_e32 vcc, v0, v191
	s_and_saveexec_b64 s[4:5], vcc
	s_cbranch_execz .LBB0_224
	s_mov_b32 s36, 1
	s_mov_b64 s[8:9], 0
	s_branch .LBB0_215

; __device__ __forceinline__ unsigned xb_ld(unsigned* p)              { return __hip_atomic_load(p, __ATOMIC_RELAXED, __HIP_MEMORY_SCOPE_AGENT); }
; __device__ __forceinline__ unsigned xb_add(unsigned* p, unsigned v) { return __hip_atomic_fetch_add(p, v, __ATOMIC_RELAXED, __HIP_MEMORY_SCOPE_AGENT); }
; #define XB_SPIN(cond, bar) do { unsigned _sp = 0; while (cond) { __builtin_amdgcn_s_sleep(1); \
;     if ((++_sp & 255u) == 0u) { if (xb_ld(&(bar)[XB_TMO])) break; if (_sp > XB_SPIN_CAP) { atomicAdd(&(bar)[XB_TMO], 1u); break; } } } } while (0)
; __device__ __forceinline__ void xcd_barrier(XcdBarrier& b) {
;     ...
;         const unsigned old = xb_add(&bar[XB_XSUB(bx)], 1u);
;         const unsigned gen = b.gen;
;         if (old + 1u == (gen + 1u) * b.nloc) {
;             __builtin_amdgcn_fence(__ATOMIC_RELEASE, "agent");
;             asm volatile("s_waitcnt vmcnt(0)" ::: "memory");
;             const unsigned og = xb_add(&bar[XB_TOP], 1u);
;             const unsigned tg = gen;
;             if (og + 1u == (tg + 1u) * b.nx) xb_add(&bar[XB_TOPGEN], 1u);
;             else XB_SPIN(xb_ld(&bar[XB_TOPGEN]) == tg, bar);
;             __builtin_amdgcn_fence(__ATOMIC_ACQUIRE, "agent");
;             xb_add(&bar[XB_XGEN(bx)], 1u);
;         } else {
;             XB_SPIN(xb_ld(&bar[XB_XGEN(bx)]) == gen, bar);
.LBB0_262:
	s_or_b64 exec, exec, s[4:5]
	s_waitcnt vmcnt(0)
	v_readfirstlane_b32 s2, v2
	v_add_u32_e32 v131, 2, v191
	s_nop 0
	v_add3_u32 v0, s2, v0, 1
	v_readlane_b32 s2, v252, 37
	s_nop 1
	v_mul_lo_u32 v2, v131, s2
	v_cmp_ne_u32_e32 vcc, v0, v2
	s_and_saveexec_b64 s[2:3], vcc
	s_xor_b64 s[2:3], exec, s[2:3]
	s_cbranch_execz .LBB0_276
	v_readlane_b32 s4, v251, 18
	v_readlane_b32 s5, v251, 19
	s_mov_b32 s7, s5
	s_movk_i32 s6, 0xd40
	v_writelane_b32 v251, s4, 18
	s_nop 1
	v_writelane_b32 v251, s5, 19
	s_lshl_b64 s[4:5], s[6:7], 2
	s_add_u32 s6, s58, s4
	s_addc_u32 s7, s59, s5
	global_load_dword v0, v1, s[6:7] sc1
	s_waitcnt vmcnt(0)
	v_cmp_eq_u32_e32 vcc, v0, v16
	s_and_saveexec_b64 s[4:5], vcc
	s_cbranch_execz .LBB0_275
	s_mov_b32 s36, 1
	s_mov_b64 s[8:9], 0
	s_branch .LBB0_266

; __device__ __forceinline__ unsigned xb_ld(unsigned* p)              { return __hip_atomic_load(p, __ATOMIC_RELAXED, __HIP_MEMORY_SCOPE_AGENT); }
; __device__ __forceinline__ unsigned xb_add(unsigned* p, unsigned v) { return __hip_atomic_fetch_add(p, v, __ATOMIC_RELAXED, __HIP_MEMORY_SCOPE_AGENT); }
; #define XB_SPIN(cond, bar) do { unsigned _sp = 0; while (cond) { __builtin_amdgcn_s_sleep(1); \
;     if ((++_sp & 255u) == 0u) { if (xb_ld(&(bar)[XB_TMO])) break; if (_sp > XB_SPIN_CAP) { atomicAdd(&(bar)[XB_TMO], 1u); break; } } } } while (0)
; __device__ __forceinline__ void xcd_barrier(XcdBarrier& b) {
;     ...
;         const unsigned old = xb_add(&bar[XB_XSUB(bx)], 1u);
;         const unsigned gen = b.gen;
;         if (old + 1u == (gen + 1u) * b.nloc) {
;             __builtin_amdgcn_fence(__ATOMIC_RELEASE, "agent");
;             asm volatile("s_waitcnt vmcnt(0)" ::: "memory");
;             const unsigned og = xb_add(&bar[XB_TOP], 1u);
;             const unsigned tg = gen;
;             if (og + 1u == (tg + 1u) * b.nx) xb_add(&bar[XB_TOPGEN], 1u);
;             else XB_SPIN(xb_ld(&bar[XB_TOPGEN]) == tg, bar);
;             __builtin_amdgcn_fence(__ATOMIC_ACQUIRE, "agent");
;             xb_add(&bar[XB_XGEN(bx)], 1u);
;         } else {
;             XB_SPIN(xb_ld(&bar[XB_XGEN(bx)]) == gen, bar);
.LBB0_313:
	s_or_b64 exec, exec, s[4:5]
	s_waitcnt vmcnt(0)
	v_readfirstlane_b32 s2, v2
	v_add_u32_e32 v72, 3, v191
	s_nop 0
	v_add3_u32 v0, s2, v0, 1
	v_readlane_b32 s2, v252, 37
	s_nop 1
	v_mul_lo_u32 v2, v72, s2
	v_cmp_ne_u32_e32 vcc, v0, v2
	s_and_saveexec_b64 s[2:3], vcc
	s_xor_b64 s[2:3], exec, s[2:3]
	s_cbranch_execz .LBB0_327
	v_readlane_b32 s4, v251, 18
	v_readlane_b32 s5, v251, 19
	s_mov_b32 s7, s5
	s_movk_i32 s6, 0xd40
	v_writelane_b32 v251, s4, 18
	s_nop 1
	v_writelane_b32 v251, s5, 19
	s_lshl_b64 s[4:5], s[6:7], 2
	s_add_u32 s6, s58, s4
	s_addc_u32 s7, s59, s5
	global_load_dword v0, v1, s[6:7] sc1
	s_waitcnt vmcnt(0)
	v_cmp_eq_u32_e32 vcc, v0, v131
	s_and_saveexec_b64 s[4:5], vcc
	s_cbranch_execz .LBB0_326
	s_mov_b32 s36, 1
	s_mov_b64 s[8:9], 0
	s_branch .LBB0_317

; __device__ __forceinline__ unsigned xb_ld(unsigned* p)              { return __hip_atomic_load(p, __ATOMIC_RELAXED, __HIP_MEMORY_SCOPE_AGENT); }
; __device__ __forceinline__ unsigned xb_add(unsigned* p, unsigned v) { return __hip_atomic_fetch_add(p, v, __ATOMIC_RELAXED, __HIP_MEMORY_SCOPE_AGENT); }
; #define XB_SPIN(cond, bar) do { unsigned _sp = 0; while (cond) { __builtin_amdgcn_s_sleep(1); \
;     if ((++_sp & 255u) == 0u) { if (xb_ld(&(bar)[XB_TMO])) break; if (_sp > XB_SPIN_CAP) { atomicAdd(&(bar)[XB_TMO], 1u); break; } } } } while (0)
; __device__ __forceinline__ void xcd_barrier(XcdBarrier& b) {
;     ...
;         const unsigned old = xb_add(&bar[XB_XSUB(bx)], 1u);
;         const unsigned gen = b.gen;
;         if (old + 1u == (gen + 1u) * b.nloc) {
;             __builtin_amdgcn_fence(__ATOMIC_RELEASE, "agent");
;             asm volatile("s_waitcnt vmcnt(0)" ::: "memory");
;             const unsigned og = xb_add(&bar[XB_TOP], 1u);
;             const unsigned tg = gen;
;             if (og + 1u == (tg + 1u) * b.nx) xb_add(&bar[XB_TOPGEN], 1u);
;             else XB_SPIN(xb_ld(&bar[XB_TOPGEN]) == tg, bar);
;             __builtin_amdgcn_fence(__ATOMIC_ACQUIRE, "agent");
;             xb_add(&bar[XB_XGEN(bx)], 1u);
;         } else {
;             XB_SPIN(xb_ld(&bar[XB_XGEN(bx)]) == gen, bar);
.LBB0_373:
	s_or_b64 exec, exec, s[4:5]
	s_waitcnt vmcnt(0)
	v_readfirstlane_b32 s2, v2
	s_nop 1
	v_add3_u32 v2, s2, v0, 1
	v_add_u32_e32 v0, 4, v191
	v_readlane_b32 s2, v252, 37
	s_nop 1
	v_mul_lo_u32 v3, v0, s2
	v_cmp_ne_u32_e32 vcc, v2, v3
	s_and_saveexec_b64 s[2:3], vcc
	s_xor_b64 s[2:3], exec, s[2:3]
	s_cbranch_execz .LBB0_387
	v_readlane_b32 s4, v251, 18
	v_readlane_b32 s5, v251, 19
	s_mov_b32 s7, s5
	s_movk_i32 s6, 0xd40
	v_writelane_b32 v251, s4, 18
	s_nop 1
	v_writelane_b32 v251, s5, 19
	s_lshl_b64 s[4:5], s[6:7], 2
	s_add_u32 s6, s58, s4
	s_addc_u32 s7, s59, s5
	global_load_dword v2, v1, s[6:7] sc1
	s_waitcnt vmcnt(0)
	v_cmp_eq_u32_e32 vcc, v2, v72
	s_and_saveexec_b64 s[4:5], vcc
	s_cbranch_execz .LBB0_386
	s_mov_b32 s36, 1
	s_mov_b64 s[8:9], 0
	s_branch .LBB0_377

; __device__ __forceinline__ unsigned xb_ld(unsigned* p)              { return __hip_atomic_load(p, __ATOMIC_RELAXED, __HIP_MEMORY_SCOPE_AGENT); }
; __device__ __forceinline__ unsigned xb_add(unsigned* p, unsigned v) { return __hip_atomic_fetch_add(p, v, __ATOMIC_RELAXED, __HIP_MEMORY_SCOPE_AGENT); }
; #define XB_SPIN(cond, bar) do { unsigned _sp = 0; while (cond) { __builtin_amdgcn_s_sleep(1); \
;     if ((++_sp & 255u) == 0u) { if (xb_ld(&(bar)[XB_TMO])) break; if (_sp > XB_SPIN_CAP) { atomicAdd(&(bar)[XB_TMO], 1u); break; } } } } while (0)
; __device__ __forceinline__ void xcd_barrier(XcdBarrier& b) {
;     ...
;         const unsigned old = xb_add(&bar[XB_XSUB(bx)], 1u);
;         const unsigned gen = b.gen;
;         if (old + 1u == (gen + 1u) * b.nloc) {
;             __builtin_amdgcn_fence(__ATOMIC_RELEASE, "agent");
;             asm volatile("s_waitcnt vmcnt(0)" ::: "memory");
;             const unsigned og = xb_add(&bar[XB_TOP], 1u);
;             const unsigned tg = gen;
;             if (og + 1u == (tg + 1u) * b.nx) xb_add(&bar[XB_TOPGEN], 1u);
;             else XB_SPIN(xb_ld(&bar[XB_TOPGEN]) == tg, bar);
;             __builtin_amdgcn_fence(__ATOMIC_ACQUIRE, "agent");
;             xb_add(&bar[XB_XGEN(bx)], 1u);
;         } else {
;             XB_SPIN(xb_ld(&bar[XB_XGEN(bx)]) == gen, bar);
.LBB0_416:
	s_or_b64 exec, exec, s[4:5]
	s_waitcnt vmcnt(0)
	v_readfirstlane_b32 s2, v3
	v_add_u32_e32 v141, 5, v191
	s_nop 0
	v_add3_u32 v2, s2, v2, 1
	v_readlane_b32 s2, v252, 37
	s_nop 1
	v_mul_lo_u32 v3, v141, s2
	v_cmp_ne_u32_e32 vcc, v2, v3
	s_and_saveexec_b64 s[2:3], vcc
	s_xor_b64 s[2:3], exec, s[2:3]
	s_cbranch_execz .LBB0_430
	v_readlane_b32 s4, v251, 18
	v_readlane_b32 s5, v251, 19
	s_mov_b32 s7, s5
	s_movk_i32 s6, 0xd40
	v_writelane_b32 v251, s4, 18
	s_nop 1
	v_writelane_b32 v251, s5, 19
	s_lshl_b64 s[4:5], s[6:7], 2
	s_add_u32 s6, s58, s4
	s_addc_u32 s7, s59, s5
	global_load_dword v2, v1, s[6:7] sc1
	s_waitcnt vmcnt(0)
	v_cmp_eq_u32_e32 vcc, v2, v0
	s_and_saveexec_b64 s[4:5], vcc
	s_cbranch_execz .LBB0_429
	s_mov_b32 s36, 1
	s_mov_b64 s[8:9], 0
	s_branch .LBB0_420

; __device__ __forceinline__ unsigned xb_ld(unsigned* p)              { return __hip_atomic_load(p, __ATOMIC_RELAXED, __HIP_MEMORY_SCOPE_AGENT); }
; __device__ __forceinline__ unsigned xb_add(unsigned* p, unsigned v) { return __hip_atomic_fetch_add(p, v, __ATOMIC_RELAXED, __HIP_MEMORY_SCOPE_AGENT); }
; #define XB_SPIN(cond, bar) do { unsigned _sp = 0; while (cond) { __builtin_amdgcn_s_sleep(1); \
;     if ((++_sp & 255u) == 0u) { if (xb_ld(&(bar)[XB_TMO])) break; if (_sp > XB_SPIN_CAP) { atomicAdd(&(bar)[XB_TMO], 1u); break; } } } } while (0)
; __device__ __forceinline__ void xcd_barrier(XcdBarrier& b) {
;     ...
;         const unsigned old = xb_add(&bar[XB_XSUB(bx)], 1u);
;         const unsigned gen = b.gen;
;         if (old + 1u == (gen + 1u) * b.nloc) {
;             __builtin_amdgcn_fence(__ATOMIC_RELEASE, "agent");
;             asm volatile("s_waitcnt vmcnt(0)" ::: "memory");
;             const unsigned og = xb_add(&bar[XB_TOP], 1u);
;             const unsigned tg = gen;
;             if (og + 1u == (tg + 1u) * b.nx) xb_add(&bar[XB_TOPGEN], 1u);
;             else XB_SPIN(xb_ld(&bar[XB_TOPGEN]) == tg, bar);
;             __builtin_amdgcn_fence(__ATOMIC_ACQUIRE, "agent");
;             xb_add(&bar[XB_XGEN(bx)], 1u);
;         } else {
;             XB_SPIN(xb_ld(&bar[XB_XGEN(bx)]) == gen, bar);
.LBB0_473:
	s_or_b64 exec, exec, s[4:5]
	s_waitcnt vmcnt(0)
	v_readfirstlane_b32 s2, v2
	s_nop 1
	v_add3_u32 v0, s2, v0, 1
	v_readlane_b32 s2, v252, 37
	s_nop 1
	v_mul_lo_u32 v2, v140, s2
	v_cmp_ne_u32_e32 vcc, v0, v2
	s_and_saveexec_b64 s[2:3], vcc
	s_xor_b64 s[2:3], exec, s[2:3]
	s_cbranch_execz .LBB0_487
	v_readlane_b32 s4, v251, 18
	v_readlane_b32 s5, v251, 19
	s_mov_b32 s7, s5
	s_movk_i32 s6, 0xd40
	v_writelane_b32 v251, s4, 18
	s_nop 1
	v_writelane_b32 v251, s5, 19
	s_lshl_b64 s[4:5], s[6:7], 2
	s_add_u32 s6, s58, s4
	s_addc_u32 s7, s59, s5
	global_load_dword v0, v1, s[6:7] sc1
	s_waitcnt vmcnt(0)
	v_cmp_eq_u32_e32 vcc, v0, v141
	s_and_saveexec_b64 s[4:5], vcc
	s_cbranch_execz .LBB0_486
	s_mov_b32 s36, 1
	s_mov_b64 s[8:9], 0
	s_branch .LBB0_477

; __device__ __forceinline__ unsigned xb_ld(unsigned* p)              { return __hip_atomic_load(p, __ATOMIC_RELAXED, __HIP_MEMORY_SCOPE_AGENT); }
; __device__ __forceinline__ unsigned xb_add(unsigned* p, unsigned v) { return __hip_atomic_fetch_add(p, v, __ATOMIC_RELAXED, __HIP_MEMORY_SCOPE_AGENT); }
; #define XB_SPIN(cond, bar) do { unsigned _sp = 0; while (cond) { __builtin_amdgcn_s_sleep(1); \
;     if ((++_sp & 255u) == 0u) { if (xb_ld(&(bar)[XB_TMO])) break; if (_sp > XB_SPIN_CAP) { atomicAdd(&(bar)[XB_TMO], 1u); break; } } } } while (0)
; __device__ __forceinline__ void xcd_barrier(XcdBarrier& b) {
;     ...
;         const unsigned old = xb_add(&bar[XB_XSUB(bx)], 1u);
;         const unsigned gen = b.gen;
;         if (old + 1u == (gen + 1u) * b.nloc) {
;             __builtin_amdgcn_fence(__ATOMIC_RELEASE, "agent");
;             asm volatile("s_waitcnt vmcnt(0)" ::: "memory");
;             const unsigned og = xb_add(&bar[XB_TOP], 1u);
;             const unsigned tg = gen;
;             if (og + 1u == (tg + 1u) * b.nx) xb_add(&bar[XB_TOPGEN], 1u);
;             else XB_SPIN(xb_ld(&bar[XB_TOPGEN]) == tg, bar);
;             __builtin_amdgcn_fence(__ATOMIC_ACQUIRE, "agent");
;             xb_add(&bar[XB_XGEN(bx)], 1u);
;         } else {
;             XB_SPIN(xb_ld(&bar[XB_XGEN(bx)]) == gen, bar);
.LBB0_564:
	s_or_b64 exec, exec, s[4:5]
	s_waitcnt vmcnt(0)
	v_readfirstlane_b32 s2, v2
	s_nop 1
	v_add3_u32 v0, s2, v0, 1
	v_readlane_b32 s2, v252, 37
	s_nop 1
	v_mul_lo_u32 v2, v14, s2
	v_cmp_ne_u32_e32 vcc, v0, v2
	s_and_saveexec_b64 s[2:3], vcc
	s_xor_b64 s[2:3], exec, s[2:3]
	s_cbranch_execz .LBB0_642
	v_readlane_b32 s4, v251, 18
	v_readlane_b32 s5, v251, 19
	s_mov_b32 s7, s5
	s_movk_i32 s6, 0xd40
	v_writelane_b32 v251, s4, 18
	s_nop 1
	v_writelane_b32 v251, s5, 19
	s_lshl_b64 s[4:5], s[6:7], 2
	s_add_u32 s6, s58, s4
	s_addc_u32 s7, s59, s5
	global_load_dword v0, v1, s[6:7] sc1
	s_waitcnt vmcnt(0)
	v_cmp_eq_u32_e32 vcc, v0, v191
	s_and_saveexec_b64 s[4:5], vcc
	s_cbranch_execz .LBB0_641
	s_mov_b32 s36, 1
	s_mov_b64 s[8:9], 0
	s_branch .LBB0_568

; __device__ __forceinline__ unsigned xb_ld(unsigned* p)              { return __hip_atomic_load(p, __ATOMIC_RELAXED, __HIP_MEMORY_SCOPE_AGENT); }
; __device__ __forceinline__ unsigned xb_add(unsigned* p, unsigned v) { return __hip_atomic_fetch_add(p, v, __ATOMIC_RELAXED, __HIP_MEMORY_SCOPE_AGENT); }
; #define XB_SPIN(cond, bar) do { unsigned _sp = 0; while (cond) { __builtin_amdgcn_s_sleep(1); \
;     if ((++_sp & 255u) == 0u) { if (xb_ld(&(bar)[XB_TMO])) break; if (_sp > XB_SPIN_CAP) { atomicAdd(&(bar)[XB_TMO], 1u); break; } } } } while (0)
; __device__ __forceinline__ void xcd_barrier(XcdBarrier& b) {
;     ...
;         const unsigned old = xb_add(&bar[XB_XSUB(bx)], 1u);
;         const unsigned gen = b.gen;
;         if (old + 1u == (gen + 1u) * b.nloc) {
;             __builtin_amdgcn_fence(__ATOMIC_RELEASE, "agent");
;             asm volatile("s_waitcnt vmcnt(0)" ::: "memory");
;             const unsigned og = xb_add(&bar[XB_TOP], 1u);
;             const unsigned tg = gen;
;             if (og + 1u == (tg + 1u) * b.nx) xb_add(&bar[XB_TOPGEN], 1u);
;             else XB_SPIN(xb_ld(&bar[XB_TOPGEN]) == tg, bar);
;             __builtin_amdgcn_fence(__ATOMIC_ACQUIRE, "agent");
;             xb_add(&bar[XB_XGEN(bx)], 1u);
;         } else {
;             XB_SPIN(xb_ld(&bar[XB_XGEN(bx)]) == gen, bar);
.LBB0_628:
	s_or_b64 exec, exec, s[4:5]
	s_waitcnt vmcnt(0)
	v_readfirstlane_b32 s2, v2
	s_nop 1
	v_add3_u32 v2, s2, v0, 1
	v_add_u32_e32 v0, 1, v191
	v_readlane_b32 s2, v252, 37
	s_nop 1
	v_mul_lo_u32 v3, v0, s2
	v_cmp_ne_u32_e32 vcc, v2, v3
	s_and_saveexec_b64 s[2:3], vcc
	s_xor_b64 s[2:3], exec, s[2:3]
	s_cbranch_execz .LBB0_659
	v_readlane_b32 s4, v251, 18
	v_readlane_b32 s5, v251, 19
	s_mov_b32 s7, s5
	s_movk_i32 s6, 0xd40
	v_writelane_b32 v251, s4, 18
	s_nop 1
	v_writelane_b32 v251, s5, 19
	s_lshl_b64 s[4:5], s[6:7], 2
	s_add_u32 s6, s58, s4
	s_addc_u32 s7, s59, s5
	global_load_dword v0, v1, s[6:7] sc1
	s_waitcnt vmcnt(0)
	v_cmp_eq_u32_e32 vcc, v0, v191
	s_and_saveexec_b64 s[4:5], vcc
	s_cbranch_execz .LBB0_658
	s_mov_b32 s36, 1
	s_mov_b64 s[8:9], 0
	s_branch .LBB0_632

; __device__ __forceinline__ unsigned xb_ld(unsigned* p)              { return __hip_atomic_load(p, __ATOMIC_RELAXED, __HIP_MEMORY_SCOPE_AGENT); }
; __device__ __forceinline__ unsigned xb_add(unsigned* p, unsigned v) { return __hip_atomic_fetch_add(p, v, __ATOMIC_RELAXED, __HIP_MEMORY_SCOPE_AGENT); }
; #define XB_SPIN(cond, bar) do { unsigned _sp = 0; while (cond) { __builtin_amdgcn_s_sleep(1); \
;     if ((++_sp & 255u) == 0u) { if (xb_ld(&(bar)[XB_TMO])) break; if (_sp > XB_SPIN_CAP) { atomicAdd(&(bar)[XB_TMO], 1u); break; } } } } while (0)
; __device__ __forceinline__ void xcd_barrier(XcdBarrier& b) {
;     ...
;         const unsigned old = xb_add(&bar[XB_XSUB(bx)], 1u);
;         const unsigned gen = b.gen;
;         if (old + 1u == (gen + 1u) * b.nloc) {
;             __builtin_amdgcn_fence(__ATOMIC_RELEASE, "agent");
;             asm volatile("s_waitcnt vmcnt(0)" ::: "memory");
;             const unsigned og = xb_add(&bar[XB_TOP], 1u);
;             const unsigned tg = gen;
;             if (og + 1u == (tg + 1u) * b.nx) xb_add(&bar[XB_TOPGEN], 1u);
;             else XB_SPIN(xb_ld(&bar[XB_TOPGEN]) == tg, bar);
;             __builtin_amdgcn_fence(__ATOMIC_ACQUIRE, "agent");
;             xb_add(&bar[XB_XGEN(bx)], 1u);
;         } else {
;             XB_SPIN(xb_ld(&bar[XB_XGEN(bx)]) == gen, bar);
.LBB0_691:
	s_or_b64 exec, exec, s[4:5]
	s_waitcnt vmcnt(0)
	v_readfirstlane_b32 s2, v2
	s_nop 1
	v_add3_u32 v0, s2, v0, 1
	v_readlane_b32 s2, v252, 37
	s_nop 1
	v_mul_lo_u32 v2, v138, s2
	v_cmp_ne_u32_e32 vcc, v0, v2
	s_and_saveexec_b64 s[2:3], vcc
	s_xor_b64 s[2:3], exec, s[2:3]
	s_cbranch_execz .LBB0_705
	v_readlane_b32 s4, v251, 18
	v_readlane_b32 s5, v251, 19
	s_mov_b32 s7, s5
	s_movk_i32 s6, 0xd40
	v_writelane_b32 v251, s4, 18
	s_nop 1
	v_writelane_b32 v251, s5, 19
	s_lshl_b64 s[4:5], s[6:7], 2
	s_add_u32 s6, s58, s4
	s_addc_u32 s7, s59, s5
	global_load_dword v0, v1, s[6:7] sc1
	s_waitcnt vmcnt(0)
	v_cmp_eq_u32_e32 vcc, v0, v14
	s_and_saveexec_b64 s[4:5], vcc
	s_cbranch_execz .LBB0_704
	s_mov_b32 s36, 1
	s_mov_b64 s[8:9], 0
	s_branch .LBB0_695

; __device__ __forceinline__ unsigned xb_ld(unsigned* p)              { return __hip_atomic_load(p, __ATOMIC_RELAXED, __HIP_MEMORY_SCOPE_AGENT); }
; __device__ __forceinline__ unsigned xb_add(unsigned* p, unsigned v) { return __hip_atomic_fetch_add(p, v, __ATOMIC_RELAXED, __HIP_MEMORY_SCOPE_AGENT); }
; #define XB_SPIN(cond, bar) do { unsigned _sp = 0; while (cond) { __builtin_amdgcn_s_sleep(1); \
;     if ((++_sp & 255u) == 0u) { if (xb_ld(&(bar)[XB_TMO])) break; if (_sp > XB_SPIN_CAP) { atomicAdd(&(bar)[XB_TMO], 1u); break; } } } } while (0)
; __device__ __forceinline__ void xcd_barrier(XcdBarrier& b) {
;     ...
;         const unsigned old = xb_add(&bar[XB_XSUB(bx)], 1u);
;         const unsigned gen = b.gen;
;         if (old + 1u == (gen + 1u) * b.nloc) {
;             __builtin_amdgcn_fence(__ATOMIC_RELEASE, "agent");
;             asm volatile("s_waitcnt vmcnt(0)" ::: "memory");
;             const unsigned og = xb_add(&bar[XB_TOP], 1u);
;             const unsigned tg = gen;
;             if (og + 1u == (tg + 1u) * b.nx) xb_add(&bar[XB_TOPGEN], 1u);
;             else XB_SPIN(xb_ld(&bar[XB_TOPGEN]) == tg, bar);
;             __builtin_amdgcn_fence(__ATOMIC_ACQUIRE, "agent");
;             xb_add(&bar[XB_XGEN(bx)], 1u);
;         } else {
;             XB_SPIN(xb_ld(&bar[XB_XGEN(bx)]) == gen, bar);
.LBB0_795:
	s_or_b64 exec, exec, s[4:5]
	s_waitcnt vmcnt(0)
	v_readfirstlane_b32 s2, v2
	s_nop 1
	v_add3_u32 v2, s2, v0, 1
	v_add_u32_e32 v0, 3, v191
	v_readlane_b32 s2, v252, 37
	s_nop 1
	v_mul_lo_u32 v3, v0, s2
	v_cmp_ne_u32_e32 vcc, v2, v3
	s_and_saveexec_b64 s[2:3], vcc
	s_xor_b64 s[2:3], exec, s[2:3]
	s_cbranch_execz .LBB0_809
	v_readlane_b32 s4, v251, 18
	v_readlane_b32 s5, v251, 19
	s_mov_b32 s7, s5
	s_movk_i32 s6, 0xd40
	v_writelane_b32 v251, s4, 18
	s_nop 1
	v_writelane_b32 v251, s5, 19
	s_lshl_b64 s[4:5], s[6:7], 2
	s_add_u32 s6, s58, s4
	s_addc_u32 s7, s59, s5
	global_load_dword v0, v1, s[6:7] sc1
	s_waitcnt vmcnt(0)
	v_cmp_eq_u32_e32 vcc, v0, v138
	s_and_saveexec_b64 s[4:5], vcc
	s_cbranch_execz .LBB0_808
	s_mov_b32 s36, 1
	s_mov_b64 s[8:9], 0
	s_branch .LBB0_799

; __device__ __forceinline__ unsigned xb_ld(unsigned* p)              { return __hip_atomic_load(p, __ATOMIC_RELAXED, __HIP_MEMORY_SCOPE_AGENT); }
; __device__ __forceinline__ unsigned xb_add(unsigned* p, unsigned v) { return __hip_atomic_fetch_add(p, v, __ATOMIC_RELAXED, __HIP_MEMORY_SCOPE_AGENT); }
; #define XB_SPIN(cond, bar) do { unsigned _sp = 0; while (cond) { __builtin_amdgcn_s_sleep(1); \
;     if ((++_sp & 255u) == 0u) { if (xb_ld(&(bar)[XB_TMO])) break; if (_sp > XB_SPIN_CAP) { atomicAdd(&(bar)[XB_TMO], 1u); break; } } } } while (0)
; __device__ __forceinline__ void xcd_barrier(XcdBarrier& b) {
;     ...
;         const unsigned old = xb_add(&bar[XB_XSUB(bx)], 1u);
;         const unsigned gen = b.gen;
;         if (old + 1u == (gen + 1u) * b.nloc) {
;             __builtin_amdgcn_fence(__ATOMIC_RELEASE, "agent");
;             asm volatile("s_waitcnt vmcnt(0)" ::: "memory");
;             const unsigned og = xb_add(&bar[XB_TOP], 1u);
;             const unsigned tg = gen;
;             if (og + 1u == (tg + 1u) * b.nx) xb_add(&bar[XB_TOPGEN], 1u);
;             else XB_SPIN(xb_ld(&bar[XB_TOPGEN]) == tg, bar);
;             __builtin_amdgcn_fence(__ATOMIC_ACQUIRE, "agent");
;             xb_add(&bar[XB_XGEN(bx)], 1u);
;         } else {
;             XB_SPIN(xb_ld(&bar[XB_XGEN(bx)]) == gen, bar);
.LBB0_882:
	s_or_b64 exec, exec, s[4:5]
	s_waitcnt vmcnt(0)
	v_readfirstlane_b32 s2, v3
	v_add_u32_e32 v0, 3, v191
	s_nop 0
	v_add3_u32 v2, s2, v2, 1
	v_readlane_b32 s2, v252, 37
	s_nop 1
	v_mul_lo_u32 v3, v141, s2
	v_cmp_ne_u32_e32 vcc, v2, v3
	s_and_saveexec_b64 s[2:3], vcc
	s_xor_b64 s[2:3], exec, s[2:3]
	s_cbranch_execz .LBB0_896
	v_readlane_b32 s4, v251, 18
	v_readlane_b32 s5, v251, 19
	s_mov_b32 s7, s5
	s_movk_i32 s6, 0xd40
	v_writelane_b32 v251, s4, 18
	s_nop 1
	v_writelane_b32 v251, s5, 19
	s_lshl_b64 s[4:5], s[6:7], 2
	s_add_u32 s6, s58, s4
	s_addc_u32 s7, s59, s5
	global_load_dword v2, v1, s[6:7] sc1
	s_waitcnt vmcnt(0)
	v_cmp_eq_u32_e32 vcc, v2, v0
	s_and_saveexec_b64 s[4:5], vcc
	s_cbranch_execz .LBB0_895
	s_mov_b32 s36, 1
	s_mov_b64 s[8:9], 0
	s_branch .LBB0_886

; __device__ __forceinline__ unsigned xb_ld(unsigned* p)              { return __hip_atomic_load(p, __ATOMIC_RELAXED, __HIP_MEMORY_SCOPE_AGENT); }
; __device__ __forceinline__ unsigned xb_add(unsigned* p, unsigned v) { return __hip_atomic_fetch_add(p, v, __ATOMIC_RELAXED, __HIP_MEMORY_SCOPE_AGENT); }
; #define XB_SPIN(cond, bar) do { unsigned _sp = 0; while (cond) { __builtin_amdgcn_s_sleep(1); \
;     if ((++_sp & 255u) == 0u) { if (xb_ld(&(bar)[XB_TMO])) break; if (_sp > XB_SPIN_CAP) { atomicAdd(&(bar)[XB_TMO], 1u); break; } } } } while (0)
; __device__ __forceinline__ void xcd_barrier(XcdBarrier& b) {
;     ...
;         const unsigned old = xb_add(&bar[XB_XSUB(bx)], 1u);
;         const unsigned gen = b.gen;
;         if (old + 1u == (gen + 1u) * b.nloc) {
;             __builtin_amdgcn_fence(__ATOMIC_RELEASE, "agent");
;             asm volatile("s_waitcnt vmcnt(0)" ::: "memory");
;             const unsigned og = xb_add(&bar[XB_TOP], 1u);
;             const unsigned tg = gen;
;             if (og + 1u == (tg + 1u) * b.nx) xb_add(&bar[XB_TOPGEN], 1u);
;             else XB_SPIN(xb_ld(&bar[XB_TOPGEN]) == tg, bar);
;             __builtin_amdgcn_fence(__ATOMIC_ACQUIRE, "agent");
;             xb_add(&bar[XB_XGEN(bx)], 1u);
;         } else {
;             XB_SPIN(xb_ld(&bar[XB_XGEN(bx)]) == gen, bar);
.LBB0_987:
	s_or_b64 exec, exec, s[4:5]
	s_waitcnt vmcnt(0)
	v_readfirstlane_b32 s2, v2
	s_nop 1
	v_add3_u32 v0, s2, v0, 1
	v_readlane_b32 s2, v252, 37
	s_nop 1
	v_mul_lo_u32 v2, v141, s2
	v_cmp_ne_u32_e32 vcc, v0, v2
	s_and_saveexec_b64 s[2:3], vcc
	s_xor_b64 s[2:3], exec, s[2:3]
	s_cbranch_execz .LBB0_1001
	v_readlane_b32 s4, v251, 18
	v_readlane_b32 s5, v251, 19
	s_mov_b32 s9, s5
	s_movk_i32 s8, 0xd40
	v_writelane_b32 v251, s4, 18
	s_nop 1
	v_writelane_b32 v251, s5, 19
	s_lshl_b64 s[4:5], s[8:9], 2
	s_add_u32 s8, s58, s4
	s_addc_u32 s9, s59, s5
	global_load_dword v0, v1, s[8:9] sc1
	s_waitcnt vmcnt(0)
	v_cmp_eq_u32_e32 vcc, v0, v140
	s_and_saveexec_b64 s[4:5], vcc
	s_cbranch_execz .LBB0_1000
	s_mov_b32 s38, 1
	s_mov_b64 s[10:11], 0
	s_branch .LBB0_991

; __device__ __forceinline__ unsigned xb_ld(unsigned* p)              { return __hip_atomic_load(p, __ATOMIC_RELAXED, __HIP_MEMORY_SCOPE_AGENT); }
; __device__ __forceinline__ unsigned xb_add(unsigned* p, unsigned v) { return __hip_atomic_fetch_add(p, v, __ATOMIC_RELAXED, __HIP_MEMORY_SCOPE_AGENT); }
; #define XB_SPIN(cond, bar) do { unsigned _sp = 0; while (cond) { __builtin_amdgcn_s_sleep(1); \
;     if ((++_sp & 255u) == 0u) { if (xb_ld(&(bar)[XB_TMO])) break; if (_sp > XB_SPIN_CAP) { atomicAdd(&(bar)[XB_TMO], 1u); break; } } } } while (0)
; __device__ __forceinline__ void xcd_barrier(XcdBarrier& b) {
;     ...
;         const unsigned old = xb_add(&bar[XB_XSUB(bx)], 1u);
;         const unsigned gen = b.gen;
;         if (old + 1u == (gen + 1u) * b.nloc) {
;             __builtin_amdgcn_fence(__ATOMIC_RELEASE, "agent");
;             asm volatile("s_waitcnt vmcnt(0)" ::: "memory");
;             const unsigned og = xb_add(&bar[XB_TOP], 1u);
;             const unsigned tg = gen;
;             if (og + 1u == (tg + 1u) * b.nx) xb_add(&bar[XB_TOPGEN], 1u);
;             else XB_SPIN(xb_ld(&bar[XB_TOPGEN]) == tg, bar);
;             __builtin_amdgcn_fence(__ATOMIC_ACQUIRE, "agent");
;             xb_add(&bar[XB_XGEN(bx)], 1u);
;         } else {
;             XB_SPIN(xb_ld(&bar[XB_XGEN(bx)]) == gen, bar);
.LBB0_1116:
	s_or_b64 exec, exec, s[8:9]
	s_waitcnt vmcnt(0)
	v_readfirstlane_b32 s2, v2
	s_nop 1
	v_add3_u32 v0, s2, v0, 1
	v_readlane_b32 s2, v252, 37
	s_nop 1
	v_mul_lo_u32 v2, v142, s2
	v_cmp_ne_u32_e32 vcc, v0, v2
	s_and_saveexec_b64 s[2:3], vcc
	s_xor_b64 s[2:3], exec, s[2:3]
	s_cbranch_execz .LBB0_1130
	v_readlane_b32 s8, v251, 18
	v_readlane_b32 s9, v251, 19
	s_mov_b32 s11, s9
	s_movk_i32 s10, 0xd40
	v_writelane_b32 v251, s8, 18
	s_nop 1
	v_writelane_b32 v251, s9, 19
	s_lshl_b64 s[8:9], s[10:11], 2
	s_add_u32 s10, s58, s8
	s_addc_u32 s11, s59, s9
	global_load_dword v0, v1, s[10:11] sc1
	s_waitcnt vmcnt(0)
	v_cmp_eq_u32_e32 vcc, v0, v141
	s_and_saveexec_b64 s[8:9], vcc
	s_cbranch_execz .LBB0_1129
	s_mov_b32 s40, 1
	s_mov_b64 s[12:13], 0
	s_branch .LBB0_1120

; __device__ __forceinline__ unsigned xb_ld(unsigned* p)              { return __hip_atomic_load(p, __ATOMIC_RELAXED, __HIP_MEMORY_SCOPE_AGENT); }
; __device__ __forceinline__ unsigned xb_add(unsigned* p, unsigned v) { return __hip_atomic_fetch_add(p, v, __ATOMIC_RELAXED, __HIP_MEMORY_SCOPE_AGENT); }
; #define XB_SPIN(cond, bar) do { unsigned _sp = 0; while (cond) { __builtin_amdgcn_s_sleep(1); \
;     if ((++_sp & 255u) == 0u) { if (xb_ld(&(bar)[XB_TMO])) break; if (_sp > XB_SPIN_CAP) { atomicAdd(&(bar)[XB_TMO], 1u); break; } } } } while (0)
; __device__ __forceinline__ void xcd_barrier(XcdBarrier& b) {
;     ...
;         const unsigned old = xb_add(&bar[XB_XSUB(bx)], 1u);
;         const unsigned gen = b.gen;
;         if (old + 1u == (gen + 1u) * b.nloc) {
;             __builtin_amdgcn_fence(__ATOMIC_RELEASE, "agent");
;             asm volatile("s_waitcnt vmcnt(0)" ::: "memory");
;             const unsigned og = xb_add(&bar[XB_TOP], 1u);
;             const unsigned tg = gen;
;             if (og + 1u == (tg + 1u) * b.nx) xb_add(&bar[XB_TOPGEN], 1u);
;             else XB_SPIN(xb_ld(&bar[XB_TOPGEN]) == tg, bar);
;             __builtin_amdgcn_fence(__ATOMIC_ACQUIRE, "agent");
;             xb_add(&bar[XB_XGEN(bx)], 1u);
;         } else {
;             XB_SPIN(xb_ld(&bar[XB_XGEN(bx)]) == gen, bar);
.LBB0_1173:
	s_or_b64 exec, exec, s[8:9]
	s_waitcnt vmcnt(0)
	v_readfirstlane_b32 s2, v2
	s_nop 1
	v_add3_u32 v0, s2, v0, 1
	v_readlane_b32 s2, v252, 37
	s_nop 1
	v_mul_lo_u32 v2, v43, s2
	v_cmp_ne_u32_e32 vcc, v0, v2
	s_and_saveexec_b64 s[2:3], vcc
	s_xor_b64 s[2:3], exec, s[2:3]
	s_cbranch_execz .LBB0_1187
	v_readlane_b32 s8, v251, 18
	v_readlane_b32 s9, v251, 19
	s_mov_b32 s11, s9
	s_movk_i32 s10, 0xd40
	v_writelane_b32 v251, s8, 18
	s_nop 1
	v_writelane_b32 v251, s9, 19
	s_lshl_b64 s[8:9], s[10:11], 2
	s_add_u32 s10, s58, s8
	s_addc_u32 s11, s59, s9
	global_load_dword v0, v1, s[10:11] sc1
	s_waitcnt vmcnt(0)
	v_cmp_eq_u32_e32 vcc, v0, v142
	s_and_saveexec_b64 s[8:9], vcc
	s_cbranch_execz .LBB0_1186
	s_mov_b32 s40, 1
	s_mov_b64 s[12:13], 0
	s_branch .LBB0_1177

; __device__ __forceinline__ unsigned xb_ld(unsigned* p)              { return __hip_atomic_load(p, __ATOMIC_RELAXED, __HIP_MEMORY_SCOPE_AGENT); }
; __device__ __forceinline__ unsigned xb_add(unsigned* p, unsigned v) { return __hip_atomic_fetch_add(p, v, __ATOMIC_RELAXED, __HIP_MEMORY_SCOPE_AGENT); }
; #define XB_SPIN(cond, bar) do { unsigned _sp = 0; while (cond) { __builtin_amdgcn_s_sleep(1); \
;     if ((++_sp & 255u) == 0u) { if (xb_ld(&(bar)[XB_TMO])) break; if (_sp > XB_SPIN_CAP) { atomicAdd(&(bar)[XB_TMO], 1u); break; } } } } while (0)
; __device__ __forceinline__ void xcd_barrier(XcdBarrier& b) {
;     ...
;         const unsigned old = xb_add(&bar[XB_XSUB(bx)], 1u);
;         const unsigned gen = b.gen;
;         if (old + 1u == (gen + 1u) * b.nloc) {
;             __builtin_amdgcn_fence(__ATOMIC_RELEASE, "agent");
;             asm volatile("s_waitcnt vmcnt(0)" ::: "memory");
;             const unsigned og = xb_add(&bar[XB_TOP], 1u);
;             const unsigned tg = gen;
;             if (og + 1u == (tg + 1u) * b.nx) xb_add(&bar[XB_TOPGEN], 1u);
;             else XB_SPIN(xb_ld(&bar[XB_TOPGEN]) == tg, bar);
;             __builtin_amdgcn_fence(__ATOMIC_ACQUIRE, "agent");
;             xb_add(&bar[XB_XGEN(bx)], 1u);
;         } else {
;             XB_SPIN(xb_ld(&bar[XB_XGEN(bx)]) == gen, bar);
.LBB0_1223:
	s_or_b64 exec, exec, s[4:5]
	s_waitcnt vmcnt(0)
	v_readfirstlane_b32 s2, v2
	s_nop 1
	v_add3_u32 v0, s2, v0, 1
	v_readlane_b32 s2, v252, 37
	s_nop 1
	v_mul_lo_u32 v2, v191, s2
	v_cmp_ne_u32_e32 vcc, v0, v2
	s_and_saveexec_b64 s[2:3], vcc
	s_xor_b64 s[2:3], exec, s[2:3]
	s_cbranch_execz .LBB0_1237
	v_readlane_b32 s4, v251, 18
	v_readlane_b32 s5, v251, 19
	s_mov_b32 s7, s5
	s_movk_i32 s6, 0xd40
	v_writelane_b32 v251, s4, 18
	s_nop 1
	v_writelane_b32 v251, s5, 19
	s_lshl_b64 s[4:5], s[6:7], 2
	s_add_u32 s6, s58, s4
	s_addc_u32 s7, s59, s5
	global_load_dword v0, v1, s[6:7] sc1
	s_waitcnt vmcnt(0)
	v_cmp_eq_u32_e32 vcc, v0, v43
	s_and_saveexec_b64 s[4:5], vcc
	s_cbranch_execz .LBB0_1236
	s_mov_b32 s36, 1
	s_mov_b64 s[8:9], 0
	s_branch .LBB0_1227

; __device__ __forceinline__ unsigned xb_ld(unsigned* p)              { return __hip_atomic_load(p, __ATOMIC_RELAXED, __HIP_MEMORY_SCOPE_AGENT); }
; __device__ __forceinline__ unsigned xb_add(unsigned* p, unsigned v) { return __hip_atomic_fetch_add(p, v, __ATOMIC_RELAXED, __HIP_MEMORY_SCOPE_AGENT); }
; #define XB_SPIN(cond, bar) do { unsigned _sp = 0; while (cond) { __builtin_amdgcn_s_sleep(1); \
;     if ((++_sp & 255u) == 0u) { if (xb_ld(&(bar)[XB_TMO])) break; if (_sp > XB_SPIN_CAP) { atomicAdd(&(bar)[XB_TMO], 1u); break; } } } } while (0)
; __device__ __forceinline__ void xcd_barrier(XcdBarrier& b) {
;     ...
;         const unsigned old = xb_add(&bar[XB_XSUB(bx)], 1u);
;         const unsigned gen = b.gen;
;         if (old + 1u == (gen + 1u) * b.nloc) {
;             __builtin_amdgcn_fence(__ATOMIC_RELEASE, "agent");
;             asm volatile("s_waitcnt vmcnt(0)" ::: "memory");
;             const unsigned og = xb_add(&bar[XB_TOP], 1u);
;             const unsigned tg = gen;
;             if (og + 1u == (tg + 1u) * b.nx) xb_add(&bar[XB_TOPGEN], 1u);
;             else XB_SPIN(xb_ld(&bar[XB_TOPGEN]) == tg, bar);
;             __builtin_amdgcn_fence(__ATOMIC_ACQUIRE, "agent");
;             xb_add(&bar[XB_XGEN(bx)], 1u);
;         } else {
;             XB_SPIN(xb_ld(&bar[XB_XGEN(bx)]) == gen, bar);
.LBB0_1341:
	s_or_b64 exec, exec, s[4:5]
	s_waitcnt vmcnt(0)
	v_readfirstlane_b32 s2, v3
	v_add_u32_e32 v26, 2, v191
	v_add_u32_e32 v0, 1, v191
	v_add3_u32 v2, s2, v2, 1
	v_readlane_b32 s2, v252, 37
	s_nop 1
	v_mul_lo_u32 v3, v26, s2
	v_cmp_ne_u32_e32 vcc, v2, v3
	s_and_saveexec_b64 s[2:3], vcc
	s_xor_b64 s[2:3], exec, s[2:3]
	s_cbranch_execz .LBB0_1355
	v_readlane_b32 s4, v251, 18
	v_readlane_b32 s5, v251, 19
	s_mov_b32 s7, s5
	s_movk_i32 s6, 0xd40
	v_writelane_b32 v251, s4, 18
	s_nop 1
	v_writelane_b32 v251, s5, 19
	s_lshl_b64 s[4:5], s[6:7], 2
	s_add_u32 s6, s58, s4
	s_addc_u32 s7, s59, s5
	global_load_dword v2, v1, s[6:7] sc1
	s_waitcnt vmcnt(0)
	v_cmp_eq_u32_e32 vcc, v2, v0
	s_and_saveexec_b64 s[4:5], vcc
	s_cbranch_execz .LBB0_1354
	s_mov_b32 s36, 1
	s_mov_b64 s[8:9], 0
	s_branch .LBB0_1345

; __device__ __forceinline__ unsigned xb_ld(unsigned* p)              { return __hip_atomic_load(p, __ATOMIC_RELAXED, __HIP_MEMORY_SCOPE_AGENT); }
; __device__ __forceinline__ unsigned xb_add(unsigned* p, unsigned v) { return __hip_atomic_fetch_add(p, v, __ATOMIC_RELAXED, __HIP_MEMORY_SCOPE_AGENT); }
; #define XB_SPIN(cond, bar) do { unsigned _sp = 0; while (cond) { __builtin_amdgcn_s_sleep(1); \
;     if ((++_sp & 255u) == 0u) { if (xb_ld(&(bar)[XB_TMO])) break; if (_sp > XB_SPIN_CAP) { atomicAdd(&(bar)[XB_TMO], 1u); break; } } } } while (0)
; __device__ __forceinline__ void xcd_barrier(XcdBarrier& b) {
;     ...
;         const unsigned old = xb_add(&bar[XB_XSUB(bx)], 1u);
;         const unsigned gen = b.gen;
;         if (old + 1u == (gen + 1u) * b.nloc) {
;             __builtin_amdgcn_fence(__ATOMIC_RELEASE, "agent");
;             asm volatile("s_waitcnt vmcnt(0)" ::: "memory");
;             const unsigned og = xb_add(&bar[XB_TOP], 1u);
;             const unsigned tg = gen;
;             if (og + 1u == (tg + 1u) * b.nx) xb_add(&bar[XB_TOPGEN], 1u);
;             else XB_SPIN(xb_ld(&bar[XB_TOPGEN]) == tg, bar);
;             __builtin_amdgcn_fence(__ATOMIC_ACQUIRE, "agent");
;             xb_add(&bar[XB_XGEN(bx)], 1u);
;         } else {
;             XB_SPIN(xb_ld(&bar[XB_XGEN(bx)]) == gen, bar);
.LBB0_1384:
	s_or_b64 exec, exec, s[4:5]
	s_waitcnt vmcnt(0)
	v_readfirstlane_b32 s2, v2
	v_add_u32_e32 v141, 3, v191
	s_nop 0
	v_add3_u32 v0, s2, v0, 1
	v_readlane_b32 s2, v252, 37
	s_nop 1
	v_mul_lo_u32 v2, v141, s2
	v_cmp_ne_u32_e32 vcc, v0, v2
	s_and_saveexec_b64 s[2:3], vcc
	s_xor_b64 s[2:3], exec, s[2:3]
	s_cbranch_execz .LBB0_1398
	v_readlane_b32 s4, v251, 18
	v_readlane_b32 s5, v251, 19
	s_mov_b32 s7, s5
	s_movk_i32 s6, 0xd40
	v_writelane_b32 v251, s4, 18
	s_nop 1
	v_writelane_b32 v251, s5, 19
	s_lshl_b64 s[4:5], s[6:7], 2
	s_add_u32 s6, s58, s4
	s_addc_u32 s7, s59, s5
	global_load_dword v0, v1, s[6:7] sc1
	s_waitcnt vmcnt(0)
	v_cmp_eq_u32_e32 vcc, v0, v26
	s_and_saveexec_b64 s[4:5], vcc
	s_cbranch_execz .LBB0_1397
	s_mov_b32 s36, 1
	s_mov_b64 s[8:9], 0
	s_branch .LBB0_1388

; __device__ __forceinline__ unsigned xb_ld(unsigned* p)              { return __hip_atomic_load(p, __ATOMIC_RELAXED, __HIP_MEMORY_SCOPE_AGENT); }
; __device__ __forceinline__ unsigned xb_add(unsigned* p, unsigned v) { return __hip_atomic_fetch_add(p, v, __ATOMIC_RELAXED, __HIP_MEMORY_SCOPE_AGENT); }
; #define XB_SPIN(cond, bar) do { unsigned _sp = 0; while (cond) { __builtin_amdgcn_s_sleep(1); \
;     if ((++_sp & 255u) == 0u) { if (xb_ld(&(bar)[XB_TMO])) break; if (_sp > XB_SPIN_CAP) { atomicAdd(&(bar)[XB_TMO], 1u); break; } } } } while (0)
; __device__ __forceinline__ void xcd_barrier(XcdBarrier& b) {
;     ...
;         const unsigned old = xb_add(&bar[XB_XSUB(bx)], 1u);
;         const unsigned gen = b.gen;
;         if (old + 1u == (gen + 1u) * b.nloc) {
;             __builtin_amdgcn_fence(__ATOMIC_RELEASE, "agent");
;             asm volatile("s_waitcnt vmcnt(0)" ::: "memory");
;             const unsigned og = xb_add(&bar[XB_TOP], 1u);
;             const unsigned tg = gen;
;             if (og + 1u == (tg + 1u) * b.nx) xb_add(&bar[XB_TOPGEN], 1u);
;             else XB_SPIN(xb_ld(&bar[XB_TOPGEN]) == tg, bar);
;             __builtin_amdgcn_fence(__ATOMIC_ACQUIRE, "agent");
;             xb_add(&bar[XB_XGEN(bx)], 1u);
;         } else {
;             XB_SPIN(xb_ld(&bar[XB_XGEN(bx)]) == gen, bar);
.LBB0_1441:
	s_or_b64 exec, exec, s[4:5]
	s_waitcnt vmcnt(0)
	v_readfirstlane_b32 s2, v2
	v_add_u32_e32 v140, 4, v191
	s_nop 0
	v_add3_u32 v0, s2, v0, 1
	v_readlane_b32 s2, v252, 37
	s_nop 1
	v_mul_lo_u32 v2, v140, s2
	v_cmp_ne_u32_e32 vcc, v0, v2
	s_and_saveexec_b64 s[2:3], vcc
	s_xor_b64 s[2:3], exec, s[2:3]
	s_cbranch_execz .LBB0_1455
	v_readlane_b32 s4, v251, 18
	v_readlane_b32 s5, v251, 19
	s_mov_b32 s7, s5
	s_movk_i32 s6, 0xd40
	v_writelane_b32 v251, s4, 18
	s_nop 1
	v_writelane_b32 v251, s5, 19
	s_lshl_b64 s[4:5], s[6:7], 2
	s_add_u32 s6, s58, s4
	s_addc_u32 s7, s59, s5
	global_load_dword v0, v1, s[6:7] sc1
	s_waitcnt vmcnt(0)
	v_cmp_eq_u32_e32 vcc, v0, v141
	s_and_saveexec_b64 s[4:5], vcc
	s_cbranch_execz .LBB0_1454
	s_mov_b32 s36, 1
	s_mov_b64 s[8:9], 0
	s_branch .LBB0_1445
